# first row pass and the row passes' slow bodies: 64-lane sums by v_permlane32/16_swap + DPP row rotations instead of six ds_bpermute round trips
# baseline (speedup 1.0000x reference)
.LBB0_138:
	s_waitcnt vmcnt(0)
	v_and_b32_e32 v81, 0xffff0000, v55
	v_and_b32_e32 v80, 0xffff0000, v54
	v_lshlrev_b32_e32 v79, 16, v55
	v_lshlrev_b32_e32 v78, 16, v54
	v_pk_mul_f32 v[32:33], v[80:81], v[80:81]
	v_and_b32_e32 v77, 0xffff0000, v53
	v_pk_fma_f32 v[32:33], v[78:79], v[78:79], v[32:33]
	v_and_b32_e32 v76, 0xffff0000, v52
	v_pk_add_f32 v[66:67], v[32:33], v[32:33] op_sel_hi:[0,1]
	v_lshlrev_b32_e32 v75, 16, v53
	v_lshlrev_b32_e32 v74, 16, v52
	v_pk_mul_f32 v[32:33], v[76:77], v[76:77]
	v_lshlrev_b32_e32 v34, 16, v51
	v_pk_fma_f32 v[32:33], v[74:75], v[74:75], v[32:33]
	v_and_b32_e32 v35, 0xffff0000, v51
	v_pk_add_f32 v[68:69], v[32:33], v[32:33] op_sel_hi:[0,1]
	v_lshlrev_b32_e32 v32, 16, v50
	v_mul_f32_e32 v65, v32, v32
	v_mul_f32_e32 v64, v34, v34
	v_and_b32_e32 v33, 0xffff0000, v50
	v_pk_fma_f32 v[82:83], v[34:35], v[34:35], v[64:65] op_sel_hi:[1,1,0]
	v_lshlrev_b32_e32 v64, 16, v48
	v_mul_f32_e32 v73, v33, v33
	v_mov_b32_e32 v72, v64
	v_and_b32_e32 v86, 0xffff0000, v48
	v_lshlrev_b32_e32 v70, 16, v49
	v_and_b32_e32 v71, 0xffff0000, v49
	v_pk_add_f32 v[72:73], v[64:65], v[72:73]
	v_mul_f32_e32 v82, v86, v86
	v_mul_f32_e32 v68, v70, v70
	v_mul_f32_e32 v66, v71, v71
	v_mul_f32_e32 v84, v64, v64
	v_mov_b32_e32 v85, v73
	v_pk_add_f32 v[72:73], v[84:85], v[82:83]
	v_pk_add_f32 v[66:67], v[68:69], v[66:67]
	v_cmp_lt_i32_e32 vcc, v205, v204
	v_pk_add_f32 v[66:67], v[72:73], v[66:67]
	s_and_b64 s[10:11], s[50:51], exec
	v_cndmask_b32_e32 v37, v203, v205, vcc
	v_add_f32_e32 v65, v66, v67
	v_lshlrev_b32_e32 v37, 2, v37
	v_cmp_lt_i32_e32 vcc, v206, v204
	s_cselect_b32 s7, s26, 8
	s_add_i32 s7, s7, s3
	s_mul_hi_i32 s11, s7, 0x6000
	v_mov_b32_e32 v66, v65
	s_nop 1
	v_permlane32_swap_b32_e32 v66, v65
	v_add_f32_e32 v65, v65, v66
	v_cndmask_b32_e32 v66, v203, v206, vcc
	v_lshlrev_b32_e32 v73, 2, v66
	v_cmp_lt_i32_e32 vcc, v207, v204
	s_mulk_i32 s7, 0x6000
	s_add_u32 s10, s34, s7
	s_addc_u32 s11, s35, s11
	v_mov_b32_e32 v66, v65
	s_nop 1
	v_permlane16_swap_b32_e32 v66, v65
	v_add_f32_e32 v65, v65, v66
	v_cndmask_b32_e32 v66, v203, v207, vcc
	v_lshlrev_b32_e32 v82, 2, v66
	v_cmp_lt_i32_e32 vcc, v208, v204
	s_movk_i32 s7, 0x3000
	v_mov_b32_e32 v98, v79
	v_mov_b32_e32 v99, v81
	s_nop 1
	v_add_f32_dpp v65, v65, v65 row_ror:8 row_mask:0xf bank_mask:0xf
	v_cndmask_b32_e32 v66, v203, v208, vcc
	v_lshlrev_b32_e32 v83, 2, v66
	v_cmp_lt_i32_e32 vcc, v209, v204
	v_mov_b32_e32 v79, v80
	s_nop 1
	v_add_f32_dpp v65, v65, v65 row_ror:4 row_mask:0xf bank_mask:0xf
	v_cndmask_b32_e32 v66, v203, v209, vcc
	v_lshlrev_b32_e32 v84, 2, v66
	v_cmp_lt_i32_e32 vcc, v210, v204
	s_nop 1
	v_add_f32_dpp v65, v65, v65 row_ror:2 row_mask:0xf bank_mask:0xf
	v_cndmask_b32_e32 v66, v203, v210, vcc
	v_lshlrev_b32_e32 v85, 2, v66
	s_nop 1
	v_add_f32_dpp v65, v65, v65 row_ror:1 row_mask:0xf bank_mask:0xf
	v_lshl_add_u64 v[66:67], s[10:11], 0, v[160:161]
	v_add_co_u32_e32 v68, vcc, s7, v66
	v_fmamk_f32 v65, v65, 0x3a800000, v200
	s_nop 0
	v_addc_co_u32_e32 v69, vcc, 0, v67, vcc
	global_load_dwordx4 v[88:91], v[68:69], off offset:-4096
	global_load_dwordx4 v[92:95], v[42:43], off
	v_rsq_f32_e32 v72, v65
	s_mov_b64 s[10:11], 0x2000
	v_lshl_add_u64 v[96:97], v[66:67], 0, s[10:11]
	v_mov_b32_e32 v65, v86
	v_pk_mul_f32 v[98:99], v[72:73], v[98:99] op_sel_hi:[0,1]
	v_pk_mul_f32 v[78:79], v[72:73], v[78:79] op_sel_hi:[0,1]
	v_pk_mul_f32 v[34:35], v[34:35], v[72:73] op_sel_hi:[1,0]
	v_pk_mul_f32 v[32:33], v[32:33], v[72:73] op_sel_hi:[1,0]
	v_pk_mul_f32 v[70:71], v[70:71], v[72:73] op_sel_hi:[1,0]
	v_pk_mul_f32 v[64:65], v[64:65], v[72:73] op_sel_hi:[1,0]
	s_mov_b64 s[10:11], 0x3000
	s_movk_i32 s7, 0x4000
	s_waitcnt vmcnt(0)
	v_pk_mul_f32 v[78:79], v[92:93], v[78:79]
	v_pk_mul_f32 v[80:81], v[94:95], v[98:99]
	v_pk_fma_f32 v[12:13], v[88:89], v[78:79], v[12:13]
	v_pk_fma_f32 v[14:15], v[90:91], v[80:81], v[14:15]
	global_load_dwordx4 v[78:81], v[96:97], off offset:1024
	global_load_dwordx4 v[88:91], v[42:43], off offset:1024
	v_mov_b32_e32 v92, v75
	v_mov_b32_e32 v93, v77
	v_mov_b32_e32 v75, v76
	v_pk_mul_f32 v[92:93], v[72:73], v[92:93] op_sel_hi:[0,1]
	v_pk_mul_f32 v[74:75], v[72:73], v[74:75] op_sel_hi:[0,1]
	s_waitcnt vmcnt(0)
	v_pk_mul_f32 v[74:75], v[88:89], v[74:75]
	v_pk_mul_f32 v[76:77], v[90:91], v[92:93]
	v_pk_fma_f32 v[8:9], v[78:79], v[74:75], v[8:9]
	v_pk_fma_f32 v[10:11], v[80:81], v[76:77], v[10:11]
	global_load_dwordx4 v[74:77], v[96:97], off offset:2048
	global_load_dwordx4 v[78:81], v[42:43], off offset:2048
	s_waitcnt vmcnt(0)
	v_pk_mul_f32 v[32:33], v[78:79], v[32:33]
	v_pk_mul_f32 v[34:35], v[80:81], v[34:35]
	v_pk_fma_f32 v[4:5], v[74:75], v[32:33], v[4:5]
	v_pk_fma_f32 v[6:7], v[76:77], v[34:35], v[6:7]
	global_load_dwordx4 v[32:35], v[96:97], off offset:3072
	global_load_dwordx4 v[74:77], v[42:43], off offset:3072
	s_waitcnt vmcnt(0)
	v_pk_mul_f32 v[64:65], v[64:65], v[74:75]
	v_pk_mul_f32 v[70:71], v[70:71], v[76:77]
	v_pk_fma_f32 v[0:1], v[32:33], v[64:65], v[0:1]
	v_pk_fma_f32 v[2:3], v[34:35], v[70:71], v[2:3]
	v_pk_mul_f32 v[32:33], v[14:15], v[14:15]
	v_pk_mul_f32 v[34:35], v[12:13], v[12:13]
	global_store_dwordx4 v160, v[12:15], s[70:71] nt
	global_store_dwordx4 v160, v[8:11], s[70:71] offset:1024 nt
	global_store_dwordx4 v160, v[4:7], s[70:71] offset:2048 nt
	global_store_dwordx4 v160, v[0:3], s[70:71] offset:3072 nt
	v_pk_mov_b32 v[64:65], v[34:35], v[32:33] op_sel:[1,0]
	v_mov_b32_e32 v35, v33
	v_pk_add_f32 v[32:33], v[64:65], v[34:35]
	v_pk_mul_f32 v[34:35], v[10:11], v[10:11]
	v_pk_add_f32 v[32:33], v[32:33], v[32:33] op_sel_hi:[0,1]
	v_pk_mul_f32 v[64:65], v[8:9], v[8:9]
	v_mul_f32_e32 v32, v4, v4
	v_pk_mov_b32 v[70:71], v[64:65], v[34:35] op_sel:[1,0]
	v_mov_b32_e32 v65, v35
	v_pk_add_f32 v[34:35], v[70:71], v[64:65]
	v_pk_fma_f32 v[64:65], v[4:5], v[4:5], v[32:33] op_sel_hi:[1,1,0]
	v_mul_f32_e32 v32, v6, v6
	v_pk_add_f32 v[34:35], v[34:35], v[34:35] op_sel_hi:[0,1]
	v_pk_fma_f32 v[70:71], v[6:7], v[6:7], v[32:33] op_sel_hi:[1,1,0]
	v_mul_f32_e32 v64, v0, v0
	v_mul_f32_e32 v70, v1, v1
	v_mul_f32_e32 v32, v2, v2
	v_mul_f32_e32 v34, v3, v3
	v_pk_add_f32 v[64:65], v[64:65], v[70:71]
	v_pk_add_f32 v[32:33], v[32:33], v[34:35]
	s_nop 0
	v_pk_add_f32 v[32:33], v[64:65], v[32:33]
	v_lshl_add_u64 v[64:65], v[66:67], 0, s[10:11]
	v_add_f32_e32 v32, v32, v33
	s_mov_b64 s[10:11], 0x4000
	v_lshl_add_u64 v[34:35], v[66:67], 0, s[10:11]
	v_add_co_u32_e32 v66, vcc, s7, v66
	v_mov_b32_e32 v33, v32
	s_nop 1
	v_permlane32_swap_b32_e32 v33, v32
	v_add_f32_e32 v32, v32, v33
	v_addc_co_u32_e32 v67, vcc, 0, v67, vcc
	global_load_dwordx4 v[70:73], v[44:45], off
	global_load_dwordx4 v[74:77], v[68:69], off
	s_mov_b32 s7, 0xfbc00000
	global_load_dwordx4 v[66:69], v[66:67], off
	v_mov_b32_e32 v33, v32
	s_nop 1
	v_permlane16_swap_b32_e32 v33, v32
	v_add_f32_e32 v32, v32, v33
	s_nop 1
	v_add_f32_dpp v32, v32, v32 row_ror:8 row_mask:0xf bank_mask:0xf
	s_nop 1
	v_add_f32_dpp v32, v32, v32 row_ror:4 row_mask:0xf bank_mask:0xf
	s_nop 1
	v_add_f32_dpp v32, v32, v32 row_ror:2 row_mask:0xf bank_mask:0xf
	s_nop 1
	v_add_f32_dpp v32, v32, v32 row_ror:1 row_mask:0xf bank_mask:0xf
	v_fmamk_f32 v32, v32, 0x3a800000, v200
	v_rsq_f32_e32 v32, v32
	s_waitcnt vmcnt(0)
	v_pk_add_f32 v[66:67], v[66:67], 1.0 op_sel_hi:[1,0]
	v_pk_mul_f32 v[78:79], v[14:15], v[32:33] op_sel_hi:[1,0]
	v_pk_mul_f32 v[80:81], v[12:13], v[32:33] op_sel_hi:[1,0]
	v_pk_mul_f32 v[72:73], v[72:73], v[78:79]
	v_pk_mul_f32 v[70:71], v[70:71], v[80:81]
	v_add_co_u32_e32 v78, vcc, s7, v46
	v_pk_add_f32 v[68:69], v[68:69], 1.0 op_sel_hi:[1,0]
	v_pk_fma_f32 v[66:67], v[66:67], v[70:71], v[74:75]
	v_addc_co_u32_e32 v79, vcc, -1, v47, vcc
	v_pk_fma_f32 v[68:69], v[68:69], v[72:73], v[76:77]
	v_cvt_pk_bf16_f32 v66, v66, v67
	v_pk_mul_f32 v[82:83], v[8:9], v[32:33] op_sel_hi:[1,0]
	v_cvt_pk_bf16_f32 v67, v68, v69
	global_store_dwordx2 v[78:79], v[66:67], off offset:-1536
	global_load_dwordx4 v[66:69], v[44:45], off offset:1024
	s_nop 0
	global_load_dwordx4 v[70:73], v[64:65], off offset:1024
	global_load_dwordx4 v[74:77], v[34:35], off offset:1024
	v_pk_mul_f32 v[80:81], v[10:11], v[32:33] op_sel_hi:[1,0]
	s_waitcnt vmcnt(2)
	v_pk_mul_f32 v[66:67], v[66:67], v[82:83]
	v_pk_mul_f32 v[68:69], v[68:69], v[80:81]
	s_waitcnt vmcnt(0)
	v_pk_add_f32 v[74:75], v[74:75], 1.0 op_sel_hi:[1,0]
	v_pk_add_f32 v[76:77], v[76:77], 1.0 op_sel_hi:[1,0]
	v_pk_fma_f32 v[66:67], v[74:75], v[66:67], v[70:71]
	v_pk_fma_f32 v[68:69], v[76:77], v[68:69], v[72:73]
	v_cvt_pk_bf16_f32 v66, v66, v67
	v_pk_mul_f32 v[82:83], v[4:5], v[32:33] op_sel_hi:[1,0]
	v_cvt_pk_bf16_f32 v67, v68, v69
	global_store_dwordx2 v[78:79], v[66:67], off offset:-1024
	global_load_dwordx4 v[66:69], v[44:45], off offset:2048
	s_nop 0
	global_load_dwordx4 v[70:73], v[64:65], off offset:2048
	global_load_dwordx4 v[74:77], v[34:35], off offset:2048
	v_pk_mul_f32 v[80:81], v[6:7], v[32:33] op_sel_hi:[1,0]
	s_waitcnt vmcnt(2)
	v_pk_mul_f32 v[66:67], v[82:83], v[66:67]
	v_pk_mul_f32 v[68:69], v[80:81], v[68:69]
	s_waitcnt vmcnt(0)
	v_pk_add_f32 v[74:75], v[74:75], 1.0 op_sel_hi:[1,0]
	v_pk_add_f32 v[76:77], v[76:77], 1.0 op_sel_hi:[1,0]
	v_pk_fma_f32 v[66:67], v[66:67], v[74:75], v[70:71]
	v_pk_fma_f32 v[68:69], v[68:69], v[76:77], v[72:73]
	v_cvt_pk_bf16_f32 v66, v66, v67
	s_nop 0
	v_cvt_pk_bf16_f32 v67, v68, v69
	global_store_dwordx2 v[78:79], v[66:67], off offset:-512
	global_load_dwordx4 v[66:69], v[44:45], off offset:3072
	s_nop 0
	global_load_dwordx4 v[70:73], v[64:65], off offset:3072
	global_load_dwordx4 v[74:77], v[34:35], off offset:3072
	v_pk_mul_f32 v[34:35], v[2:3], v[32:33] op_sel_hi:[1,0]
	v_pk_mul_f32 v[32:33], v[0:1], v[32:33] op_sel_hi:[1,0]
	s_waitcnt vmcnt(2)
	v_pk_mul_f32 v[34:35], v[34:35], v[68:69]
	v_pk_mul_f32 v[32:33], v[32:33], v[66:67]
	s_waitcnt vmcnt(0)
	v_pk_add_f32 v[66:67], v[74:75], 1.0 op_sel_hi:[1,0]
	v_pk_add_f32 v[64:65], v[76:77], 1.0 op_sel_hi:[1,0]
	v_pk_fma_f32 v[32:33], v[32:33], v[66:67], v[70:71]
	v_pk_fma_f32 v[34:35], v[34:35], v[64:65], v[72:73]
	v_cvt_pk_bf16_f32 v32, v32, v33
	s_nop 0
	v_cvt_pk_bf16_f32 v33, v34, v35
	global_store_dwordx2 v[78:79], v[32:33], off
	s_and_b64 vcc, exec, s[8:9]
	s_cbranch_vccnz .LBB0_131
.LBB0_139:
	s_waitcnt vmcnt(0)
	v_and_b32_e32 v81, 0xffff0000, v63
	v_and_b32_e32 v80, 0xffff0000, v62
	v_lshlrev_b32_e32 v79, 16, v63
	v_lshlrev_b32_e32 v78, 16, v62
	v_pk_mul_f32 v[32:33], v[80:81], v[80:81]
	v_and_b32_e32 v77, 0xffff0000, v61
	v_pk_fma_f32 v[32:33], v[78:79], v[78:79], v[32:33]
	v_and_b32_e32 v76, 0xffff0000, v60
	v_pk_add_f32 v[64:65], v[32:33], v[32:33] op_sel_hi:[0,1]
	v_lshlrev_b32_e32 v75, 16, v61
	v_lshlrev_b32_e32 v74, 16, v60
	v_pk_mul_f32 v[32:33], v[76:77], v[76:77]
	v_lshlrev_b32_e32 v34, 16, v59
	v_pk_fma_f32 v[32:33], v[74:75], v[74:75], v[32:33]
	v_lshlrev_b32_e32 v68, 16, v56
	v_pk_add_f32 v[66:67], v[32:33], v[32:33] op_sel_hi:[0,1]
	v_lshlrev_b32_e32 v32, 16, v58
	v_and_b32_e32 v33, 0xffff0000, v58
	v_mul_f32_e32 v69, v32, v32
	v_mul_f32_e32 v73, v33, v33
	v_and_b32_e32 v35, 0xffff0000, v59
	v_mul_f32_e32 v64, v34, v34
	v_mov_b32_e32 v72, v68
	v_pk_fma_f32 v[82:83], v[34:35], v[34:35], v[64:65] op_sel_hi:[1,1,0]
	v_and_b32_e32 v86, 0xffff0000, v56
	v_lshlrev_b32_e32 v70, 16, v57
	v_and_b32_e32 v71, 0xffff0000, v57
	v_pk_add_f32 v[72:73], v[68:69], v[72:73]
	v_mul_f32_e32 v82, v86, v86
	v_mul_f32_e32 v66, v70, v70
	v_mul_f32_e32 v64, v71, v71
	v_mul_f32_e32 v84, v68, v68
	v_mov_b32_e32 v85, v73
	v_pk_add_f32 v[72:73], v[84:85], v[82:83]
	v_pk_add_f32 v[64:65], v[66:67], v[64:65]
	v_cmp_lt_i32_e32 vcc, v205, v204
	v_pk_add_f32 v[64:65], v[72:73], v[64:65]
	s_and_b64 s[8:9], s[68:69], exec
	v_cndmask_b32_e32 v37, v203, v205, vcc
	v_add_f32_e32 v64, v64, v65
	v_lshlrev_b32_e32 v37, 2, v37
	v_cmp_lt_i32_e32 vcc, v206, v204
	s_cselect_b32 s7, s66, 8
	s_add_i32 s7, s7, s3
	s_mul_hi_i32 s9, s7, 0x6000
	v_mov_b32_e32 v65, v64
	s_nop 1
	v_permlane32_swap_b32_e32 v65, v64
	v_add_f32_e32 v64, v64, v65
	v_cndmask_b32_e32 v65, v203, v206, vcc
	v_lshlrev_b32_e32 v73, 2, v65
	v_cmp_lt_i32_e32 vcc, v207, v204
	s_mulk_i32 s7, 0x6000
	s_add_u32 s8, s34, s7
	s_addc_u32 s9, s35, s9
	v_mov_b32_e32 v65, v64
	s_nop 1
	v_permlane16_swap_b32_e32 v65, v64
	v_add_f32_e32 v64, v64, v65
	v_cndmask_b32_e32 v65, v203, v207, vcc
	v_lshlrev_b32_e32 v82, 2, v65
	v_cmp_lt_i32_e32 vcc, v208, v204
	s_movk_i32 s7, 0x3000
	v_mov_b32_e32 v98, v79
	v_mov_b32_e32 v99, v81
	s_nop 1
	v_add_f32_dpp v64, v64, v64 row_ror:8 row_mask:0xf bank_mask:0xf
	v_cndmask_b32_e32 v65, v203, v208, vcc
	v_lshlrev_b32_e32 v83, 2, v65
	v_cmp_lt_i32_e32 vcc, v209, v204
	v_mov_b32_e32 v79, v80
	v_mov_b32_e32 v69, v86
	s_nop 1
	v_add_f32_dpp v64, v64, v64 row_ror:4 row_mask:0xf bank_mask:0xf
	v_cndmask_b32_e32 v65, v203, v209, vcc
	v_lshlrev_b32_e32 v84, 2, v65
	v_cmp_lt_i32_e32 vcc, v210, v204
	s_nop 1
	v_add_f32_dpp v64, v64, v64 row_ror:2 row_mask:0xf bank_mask:0xf
	v_cndmask_b32_e32 v65, v203, v210, vcc
	v_lshlrev_b32_e32 v85, 2, v65
	s_nop 1
	v_add_f32_dpp v64, v64, v64 row_ror:1 row_mask:0xf bank_mask:0xf
	v_fmamk_f32 v64, v64, 0x3a800000, v200
	v_rsq_f32_e32 v72, v64
	v_lshl_add_u64 v[64:65], s[8:9], 0, v[160:161]
	v_add_co_u32_e32 v66, vcc, s7, v64
	s_mov_b64 s[8:9], 0x2000
	s_nop 0
	v_addc_co_u32_e32 v67, vcc, 0, v65, vcc
	global_load_dwordx4 v[88:91], v[66:67], off offset:-4096
	global_load_dwordx4 v[92:95], v[42:43], off
	v_pk_mul_f32 v[98:99], v[72:73], v[98:99] op_sel_hi:[0,1]
	v_pk_mul_f32 v[78:79], v[72:73], v[78:79] op_sel_hi:[0,1]
	v_lshl_add_u64 v[96:97], v[64:65], 0, s[8:9]
	v_pk_mul_f32 v[34:35], v[34:35], v[72:73] op_sel_hi:[1,0]
	v_pk_mul_f32 v[32:33], v[32:33], v[72:73] op_sel_hi:[1,0]
	v_pk_mul_f32 v[70:71], v[70:71], v[72:73] op_sel_hi:[1,0]
	v_pk_mul_f32 v[68:69], v[68:69], v[72:73] op_sel_hi:[1,0]
	s_ashr_i32 s7, s6, 31
	s_lshl_b64 s[6:7], s[6:7], 11
	s_mov_b64 s[8:9], 0x3000
	s_waitcnt vmcnt(0)
	v_pk_mul_f32 v[78:79], v[92:93], v[78:79]
	v_pk_mul_f32 v[80:81], v[94:95], v[98:99]
	v_pk_fma_f32 v[16:17], v[88:89], v[78:79], v[16:17]
	v_pk_fma_f32 v[18:19], v[90:91], v[80:81], v[18:19]
	global_load_dwordx4 v[78:81], v[96:97], off offset:1024
	global_load_dwordx4 v[88:91], v[42:43], off offset:1024
	v_mov_b32_e32 v92, v75
	v_mov_b32_e32 v93, v77
	v_mov_b32_e32 v75, v76
	v_pk_mul_f32 v[92:93], v[72:73], v[92:93] op_sel_hi:[0,1]
	v_pk_mul_f32 v[74:75], v[72:73], v[74:75] op_sel_hi:[0,1]
	s_waitcnt vmcnt(0)
	v_pk_mul_f32 v[74:75], v[88:89], v[74:75]
	v_pk_mul_f32 v[76:77], v[90:91], v[92:93]
	v_pk_fma_f32 v[20:21], v[78:79], v[74:75], v[20:21]
	v_pk_fma_f32 v[22:23], v[80:81], v[76:77], v[22:23]
	global_load_dwordx4 v[74:77], v[96:97], off offset:2048
	global_load_dwordx4 v[78:81], v[42:43], off offset:2048
	s_waitcnt vmcnt(0)
	v_pk_mul_f32 v[32:33], v[78:79], v[32:33]
	v_pk_mul_f32 v[34:35], v[80:81], v[34:35]
	v_pk_fma_f32 v[24:25], v[74:75], v[32:33], v[24:25]
	v_pk_fma_f32 v[26:27], v[76:77], v[34:35], v[26:27]
	global_load_dwordx4 v[32:35], v[96:97], off offset:3072
	global_load_dwordx4 v[74:77], v[42:43], off offset:3072
	s_waitcnt vmcnt(0)
	v_pk_mul_f32 v[68:69], v[68:69], v[74:75]
	v_pk_mul_f32 v[70:71], v[70:71], v[76:77]
	v_pk_fma_f32 v[28:29], v[32:33], v[68:69], v[28:29]
	v_pk_fma_f32 v[30:31], v[34:35], v[70:71], v[30:31]
	v_pk_mul_f32 v[32:33], v[18:19], v[18:19]
	v_pk_mul_f32 v[34:35], v[16:17], v[16:17]
	global_store_dwordx4 v160, v[16:19], s[64:65] nt
	global_store_dwordx4 v160, v[20:23], s[64:65] offset:1024 nt
	global_store_dwordx4 v160, v[24:27], s[64:65] offset:2048 nt
	global_store_dwordx4 v160, v[28:31], s[64:65] offset:3072 nt
	v_pk_mov_b32 v[68:69], v[34:35], v[32:33] op_sel:[1,0]
	v_mov_b32_e32 v35, v33
	v_pk_add_f32 v[32:33], v[68:69], v[34:35]
	v_pk_mul_f32 v[34:35], v[22:23], v[22:23]
	v_pk_add_f32 v[32:33], v[32:33], v[32:33] op_sel_hi:[0,1]
	v_pk_mul_f32 v[68:69], v[20:21], v[20:21]
	v_mul_f32_e32 v32, v24, v24
	v_pk_mov_b32 v[70:71], v[68:69], v[34:35] op_sel:[1,0]
	v_mov_b32_e32 v69, v35
	v_pk_add_f32 v[34:35], v[70:71], v[68:69]
	v_pk_fma_f32 v[68:69], v[24:25], v[24:25], v[32:33] op_sel_hi:[1,1,0]
	v_mul_f32_e32 v32, v26, v26
	v_pk_add_f32 v[34:35], v[34:35], v[34:35] op_sel_hi:[0,1]
	v_pk_fma_f32 v[70:71], v[26:27], v[26:27], v[32:33] op_sel_hi:[1,1,0]
	v_mul_f32_e32 v68, v28, v28
	v_mul_f32_e32 v70, v29, v29
	v_mul_f32_e32 v32, v30, v30
	v_mul_f32_e32 v34, v31, v31
	v_pk_add_f32 v[68:69], v[68:69], v[70:71]
	v_pk_add_f32 v[32:33], v[32:33], v[34:35]
	v_lshl_add_u64 v[70:71], v[64:65], 0, s[8:9]
	v_pk_add_f32 v[32:33], v[68:69], v[32:33]
	s_mov_b64 s[8:9], 0x4000
	v_add_f32_e32 v32, v32, v33
	v_lshl_add_u64 v[68:69], v[64:65], 0, s[8:9]
	v_mov_b32_e32 v33, v32
	s_nop 1
	v_permlane32_swap_b32_e32 v33, v32
	v_add_f32_e32 v32, v32, v33
	global_load_dwordx4 v[72:75], v[44:45], off
	global_load_dwordx4 v[76:79], v[66:67], off
	v_mov_b32_e32 v33, v32
	s_nop 1
	v_permlane16_swap_b32_e32 v33, v32
	v_add_f32_e32 v32, v32, v33
	s_nop 1
	v_add_f32_dpp v32, v32, v32 row_ror:8 row_mask:0xf bank_mask:0xf
	s_nop 1
	v_add_f32_dpp v32, v32, v32 row_ror:4 row_mask:0xf bank_mask:0xf
	s_nop 1
	v_add_f32_dpp v32, v32, v32 row_ror:2 row_mask:0xf bank_mask:0xf
	s_nop 1
	v_add_f32_dpp v32, v32, v32 row_ror:1 row_mask:0xf bank_mask:0xf
	v_fmamk_f32 v32, v32, 0x3a800000, v200
	v_rsq_f32_e32 v34, v32
	v_lshl_add_u64 v[32:33], v[40:41], 0, s[6:7]
	s_movk_i32 s6, 0x4000
	v_add_co_u32_e32 v64, vcc, s6, v64
	v_pk_mul_f32 v[82:83], v[16:17], v[34:35] op_sel_hi:[1,0]
	s_nop 0
	v_addc_co_u32_e32 v65, vcc, 0, v65, vcc
	global_load_dwordx4 v[64:67], v[64:65], off
	v_pk_mul_f32 v[80:81], v[18:19], v[34:35] op_sel_hi:[1,0]
	s_waitcnt vmcnt(2)
	v_pk_mul_f32 v[72:73], v[72:73], v[82:83]
	v_pk_mul_f32 v[74:75], v[74:75], v[80:81]
	v_pk_mul_f32 v[82:83], v[20:21], v[34:35] op_sel_hi:[1,0]
	v_pk_mul_f32 v[80:81], v[22:23], v[34:35] op_sel_hi:[1,0]
	s_waitcnt vmcnt(0)
	v_pk_add_f32 v[64:65], v[64:65], 1.0 op_sel_hi:[1,0]
	v_pk_add_f32 v[66:67], v[66:67], 1.0 op_sel_hi:[1,0]
	v_pk_fma_f32 v[64:65], v[64:65], v[72:73], v[76:77]
	v_pk_fma_f32 v[66:67], v[66:67], v[74:75], v[78:79]
	v_cvt_pk_bf16_f32 v64, v64, v65
	s_nop 0
	v_cvt_pk_bf16_f32 v65, v66, v67
	global_store_dwordx2 v[32:33], v[64:65], off
	global_load_dwordx4 v[64:67], v[44:45], off offset:1024
	s_nop 0
	global_load_dwordx4 v[72:75], v[70:71], off offset:1024
	global_load_dwordx4 v[76:79], v[68:69], off offset:1024
	s_waitcnt vmcnt(2)
	v_pk_mul_f32 v[64:65], v[64:65], v[82:83]
	v_pk_mul_f32 v[66:67], v[66:67], v[80:81]
	s_waitcnt vmcnt(0)
	v_pk_add_f32 v[76:77], v[76:77], 1.0 op_sel_hi:[1,0]
	v_pk_add_f32 v[78:79], v[78:79], 1.0 op_sel_hi:[1,0]
	v_pk_fma_f32 v[64:65], v[76:77], v[64:65], v[72:73]
	v_pk_fma_f32 v[66:67], v[78:79], v[66:67], v[74:75]
	v_cvt_pk_bf16_f32 v64, v64, v65
	v_pk_mul_f32 v[82:83], v[24:25], v[34:35] op_sel_hi:[1,0]
	v_cvt_pk_bf16_f32 v65, v66, v67
	global_store_dwordx2 v[32:33], v[64:65], off offset:512
	global_load_dwordx4 v[64:67], v[44:45], off offset:2048
	s_nop 0
	global_load_dwordx4 v[72:75], v[70:71], off offset:2048
	global_load_dwordx4 v[76:79], v[68:69], off offset:2048
	v_pk_mul_f32 v[80:81], v[26:27], v[34:35] op_sel_hi:[1,0]
	s_waitcnt vmcnt(2)
	v_pk_mul_f32 v[64:65], v[82:83], v[64:65]
	v_pk_mul_f32 v[66:67], v[80:81], v[66:67]
	s_waitcnt vmcnt(0)
	v_pk_add_f32 v[76:77], v[76:77], 1.0 op_sel_hi:[1,0]
	v_pk_add_f32 v[78:79], v[78:79], 1.0 op_sel_hi:[1,0]
	v_pk_fma_f32 v[64:65], v[64:65], v[76:77], v[72:73]
	v_pk_fma_f32 v[66:67], v[66:67], v[78:79], v[74:75]
	v_cvt_pk_bf16_f32 v64, v64, v65
	s_nop 0
	v_cvt_pk_bf16_f32 v65, v66, v67
	global_store_dwordx2 v[32:33], v[64:65], off offset:1024
	global_load_dwordx4 v[64:67], v[44:45], off offset:3072
	s_nop 0
	global_load_dwordx4 v[70:73], v[70:71], off offset:3072
	s_nop 0
	global_load_dwordx4 v[74:77], v[68:69], off offset:3072
	v_pk_mul_f32 v[68:69], v[30:31], v[34:35] op_sel_hi:[1,0]
	v_pk_mul_f32 v[34:35], v[28:29], v[34:35] op_sel_hi:[1,0]
	s_waitcnt vmcnt(2)
	v_pk_mul_f32 v[34:35], v[34:35], v[64:65]
	v_pk_mul_f32 v[64:65], v[68:69], v[66:67]
	s_waitcnt vmcnt(0)
	v_pk_add_f32 v[68:69], v[74:75], 1.0 op_sel_hi:[1,0]
	v_pk_add_f32 v[66:67], v[76:77], 1.0 op_sel_hi:[1,0]
	v_pk_fma_f32 v[34:35], v[34:35], v[68:69], v[70:71]
	v_pk_fma_f32 v[64:65], v[64:65], v[66:67], v[72:73]
	v_cvt_pk_bf16_f32 v34, v34, v35
	s_nop 0
	v_cvt_pk_bf16_f32 v35, v64, v65
	global_store_dwordx2 v[32:33], v[34:35], off offset:1536
	s_branch .LBB0_131

.LBB0_153:
	v_cndmask_b32_e64 v32, 0, 1, s[4:5]
	s_and_b64 vcc, exec, s[8:9]
	v_cmp_ne_u32_e64 s[8:9], 1, v32
	s_cbranch_vccnz .LBB0_156
	s_waitcnt vmcnt(3)
	v_and_b32_e32 v77, 0xffff0000, v55
	v_and_b32_e32 v76, 0xffff0000, v54
	v_lshlrev_b32_e32 v75, 16, v55
	v_lshlrev_b32_e32 v74, 16, v54
	v_pk_mul_f32 v[32:33], v[76:77], v[76:77]
	s_waitcnt vmcnt(2)
	v_and_b32_e32 v73, 0xffff0000, v53
	v_pk_fma_f32 v[32:33], v[74:75], v[74:75], v[32:33]
	v_and_b32_e32 v72, 0xffff0000, v52
	v_pk_add_f32 v[68:69], v[32:33], v[32:33] op_sel_hi:[0,1]
	v_lshlrev_b32_e32 v71, 16, v53
	v_lshlrev_b32_e32 v70, 16, v52
	v_pk_mul_f32 v[32:33], v[72:73], v[72:73]
	s_waitcnt vmcnt(1)
	v_lshlrev_b32_e32 v34, 16, v51
	v_pk_fma_f32 v[32:33], v[70:71], v[70:71], v[32:33]
	v_and_b32_e32 v35, 0xffff0000, v51
	v_pk_add_f32 v[78:79], v[32:33], v[32:33] op_sel_hi:[0,1]
	v_lshlrev_b32_e32 v32, 16, v50
	v_mul_f32_e32 v65, v32, v32
	v_mul_f32_e32 v64, v34, v34
	v_and_b32_e32 v33, 0xffff0000, v50
	v_pk_fma_f32 v[84:85], v[34:35], v[34:35], v[64:65] op_sel_hi:[1,1,0]
	s_waitcnt vmcnt(0)
	v_lshlrev_b32_e32 v64, 16, v48
	v_mul_f32_e32 v81, v33, v33
	v_mov_b32_e32 v80, v64
	v_and_b32_e32 v82, 0xffff0000, v48
	v_lshlrev_b32_e32 v66, 16, v49
	v_and_b32_e32 v67, 0xffff0000, v49
	v_pk_add_f32 v[80:81], v[64:65], v[80:81]
	v_mul_f32_e32 v84, v82, v82
	v_mul_f32_e32 v78, v66, v66
	v_mul_f32_e32 v68, v67, v67
	v_mul_f32_e32 v86, v64, v64
	v_mov_b32_e32 v87, v81
	v_pk_add_f32 v[80:81], v[86:87], v[84:85]
	v_pk_add_f32 v[68:69], v[78:79], v[68:69]
	v_cmp_lt_i32_e32 vcc, v205, v204
	v_pk_add_f32 v[68:69], v[80:81], v[68:69]
	s_and_b64 s[46:47], s[50:51], exec
	v_cndmask_b32_e32 v37, v203, v205, vcc
	v_add_f32_e32 v65, v68, v69
	v_lshlrev_b32_e32 v37, 2, v37
	v_cmp_lt_i32_e32 vcc, v206, v204
	s_cselect_b32 s25, s26, 8
	s_add_i32 s26, s25, s3
	s_mul_hi_i32 s27, s26, 0x6000
	v_mov_b32_e32 v68, v65
	s_nop 1
	v_permlane32_swap_b32_e32 v68, v65
	v_add_f32_e32 v65, v65, v68
	v_cndmask_b32_e32 v68, v203, v206, vcc
	v_lshlrev_b32_e32 v69, 2, v68
	v_cmp_lt_i32_e32 vcc, v207, v204
	s_mulk_i32 s26, 0x6000
	s_add_u32 s26, s34, s26
	s_addc_u32 s27, s35, s27
	v_mov_b32_e32 v68, v65
	s_nop 1
	v_permlane16_swap_b32_e32 v68, v65
	v_add_f32_e32 v65, v65, v68
	v_cndmask_b32_e32 v68, v203, v207, vcc
	v_lshlrev_b32_e32 v78, 2, v68
	v_cmp_lt_i32_e32 vcc, v208, v204
	v_lshl_add_u64 v[84:85], s[26:27], 0, v[160:161]
	s_mov_b64 s[26:27], 0x5000
	v_lshl_add_u64 v[92:93], v[84:85], 0, s[26:27]
	s_nop 1
	v_add_f32_dpp v65, v65, v65 row_ror:8 row_mask:0xf bank_mask:0xf
	v_cndmask_b32_e32 v68, v203, v208, vcc
	v_lshlrev_b32_e32 v79, 2, v68
	v_cmp_lt_i32_e32 vcc, v209, v204
	s_movk_i32 s26, 0x5000
	v_mov_b32_e32 v94, v75
	v_mov_b32_e32 v95, v77
	s_nop 1
	v_add_f32_dpp v65, v65, v65 row_ror:4 row_mask:0xf bank_mask:0xf
	v_cndmask_b32_e32 v68, v203, v209, vcc
	v_lshlrev_b32_e32 v80, 2, v68
	v_cmp_lt_i32_e32 vcc, v210, v204
	v_mov_b32_e32 v75, v76
	s_nop 1
	v_add_f32_dpp v65, v65, v65 row_ror:2 row_mask:0xf bank_mask:0xf
	v_cndmask_b32_e32 v68, v203, v210, vcc
	v_add_co_u32_e32 v84, vcc, s26, v84
	v_lshlrev_b32_e32 v81, 2, v68
	s_nop 0
	v_addc_co_u32_e32 v85, vcc, 0, v85, vcc
	global_load_dwordx4 v[84:87], v[84:85], off
	s_nop 0
	global_load_dwordx4 v[88:91], v[42:43], off
	s_and_b64 vcc, exec, s[8:9]
	s_nop 1
	v_add_f32_dpp v65, v65, v65 row_ror:1 row_mask:0xf bank_mask:0xf
	v_fmamk_f32 v65, v65, 0x3a800000, v200
	v_rsq_f32_e32 v68, v65
	v_mov_b32_e32 v65, v82
	v_pk_mul_f32 v[94:95], v[68:69], v[94:95] op_sel_hi:[0,1]
	v_pk_mul_f32 v[74:75], v[68:69], v[74:75] op_sel_hi:[0,1]
	v_pk_mul_f32 v[34:35], v[34:35], v[68:69] op_sel_hi:[1,0]
	v_pk_mul_f32 v[32:33], v[32:33], v[68:69] op_sel_hi:[1,0]
	v_pk_mul_f32 v[66:67], v[66:67], v[68:69] op_sel_hi:[1,0]
	v_pk_mul_f32 v[64:65], v[64:65], v[68:69] op_sel_hi:[1,0]
	s_waitcnt vmcnt(0)
	v_pk_mul_f32 v[74:75], v[88:89], v[74:75]
	v_pk_mul_f32 v[76:77], v[90:91], v[94:95]
	v_pk_fma_f32 v[12:13], v[84:85], v[74:75], v[12:13]
	v_pk_fma_f32 v[14:15], v[86:87], v[76:77], v[14:15]
	global_load_dwordx4 v[74:77], v[92:93], off offset:1024
	global_load_dwordx4 v[84:87], v[42:43], off offset:1024
	v_mov_b32_e32 v88, v71
	v_mov_b32_e32 v89, v73
	v_mov_b32_e32 v71, v72
	v_pk_mul_f32 v[88:89], v[68:69], v[88:89] op_sel_hi:[0,1]
	v_pk_mul_f32 v[70:71], v[68:69], v[70:71] op_sel_hi:[0,1]
	s_waitcnt vmcnt(0)
	v_pk_mul_f32 v[70:71], v[84:85], v[70:71]
	v_pk_mul_f32 v[72:73], v[86:87], v[88:89]
	v_pk_fma_f32 v[8:9], v[74:75], v[70:71], v[8:9]
	v_pk_fma_f32 v[10:11], v[76:77], v[72:73], v[10:11]
	global_load_dwordx4 v[70:73], v[92:93], off offset:2048
	global_load_dwordx4 v[74:77], v[42:43], off offset:2048
	s_waitcnt vmcnt(0)
	v_pk_mul_f32 v[32:33], v[74:75], v[32:33]
	v_pk_mul_f32 v[34:35], v[76:77], v[34:35]
	v_pk_fma_f32 v[4:5], v[70:71], v[32:33], v[4:5]
	v_pk_fma_f32 v[6:7], v[72:73], v[34:35], v[6:7]
	global_load_dwordx4 v[32:35], v[92:93], off offset:3072
	global_load_dwordx4 v[70:73], v[42:43], off offset:3072
	s_waitcnt vmcnt(0)
	v_pk_mul_f32 v[64:65], v[64:65], v[70:71]
	v_pk_mul_f32 v[66:67], v[66:67], v[72:73]
	v_pk_fma_f32 v[0:1], v[32:33], v[64:65], v[0:1]
	v_pk_fma_f32 v[2:3], v[34:35], v[66:67], v[2:3]
	global_store_dwordx4 v160, v[12:15], s[66:67] nt
	global_store_dwordx4 v160, v[8:11], s[66:67] offset:1024 nt
	global_store_dwordx4 v160, v[4:7], s[66:67] offset:2048 nt
	global_store_dwordx4 v160, v[0:3], s[66:67] offset:3072 nt
	s_cbranch_vccnz .LBB0_156
	v_pk_mul_f32 v[32:33], v[14:15], v[14:15]
	v_pk_mul_f32 v[34:35], v[12:13], v[12:13]
	s_add_i32 s25, s25, s13
	v_pk_mov_b32 v[64:65], v[34:35], v[32:33] op_sel:[1,0]
	v_mov_b32_e32 v35, v33
	v_pk_add_f32 v[32:33], v[64:65], v[34:35]
	v_pk_mul_f32 v[34:35], v[10:11], v[10:11]
	v_pk_add_f32 v[32:33], v[32:33], v[32:33] op_sel_hi:[0,1]
	v_pk_mul_f32 v[64:65], v[8:9], v[8:9]
	v_mul_f32_e32 v32, v4, v4
	v_pk_mov_b32 v[66:67], v[64:65], v[34:35] op_sel:[1,0]
	v_mov_b32_e32 v65, v35
	v_pk_add_f32 v[34:35], v[66:67], v[64:65]
	v_pk_fma_f32 v[64:65], v[4:5], v[4:5], v[32:33] op_sel_hi:[1,1,0]
	v_mul_f32_e32 v32, v6, v6
	v_pk_add_f32 v[34:35], v[34:35], v[34:35] op_sel_hi:[0,1]
	v_pk_fma_f32 v[66:67], v[6:7], v[6:7], v[32:33] op_sel_hi:[1,1,0]
	v_mul_f32_e32 v64, v0, v0
	v_mul_f32_e32 v66, v1, v1
	v_mul_f32_e32 v32, v2, v2
	v_mul_f32_e32 v34, v3, v3
	v_pk_add_f32 v[64:65], v[64:65], v[66:67]
	v_pk_add_f32 v[32:33], v[32:33], v[34:35]
	s_mul_hi_i32 s27, s25, 0x6000
	v_pk_add_f32 v[32:33], v[64:65], v[32:33]
	s_mulk_i32 s25, 0x6000
	v_add_f32_e32 v32, v32, v33
	s_add_u32 s26, s34, s25
	s_addc_u32 s27, s35, s27
	v_lshl_add_u64 v[72:73], s[26:27], 0, v[160:161]
	v_lshl_add_u64 v[34:35], v[72:73], 0, s[30:31]
	v_add_co_u32_e32 v72, vcc, s58, v72
	v_mov_b32_e32 v33, v32
	s_nop 1
	v_permlane32_swap_b32_e32 v33, v32
	v_add_f32_e32 v32, v32, v33
	v_addc_co_u32_e32 v73, vcc, 0, v73, vcc
	global_load_dwordx4 v[64:67], v[44:45], off
	global_load_dwordx4 v[68:71], v160, s[26:27]
	s_mov_b32 s25, 0xfbc00000
	global_load_dwordx4 v[72:75], v[72:73], off
	v_mov_b32_e32 v33, v32
	s_nop 1
	v_permlane16_swap_b32_e32 v33, v32
	v_add_f32_e32 v32, v32, v33
	s_nop 1
	v_add_f32_dpp v32, v32, v32 row_ror:8 row_mask:0xf bank_mask:0xf
	s_nop 1
	v_add_f32_dpp v32, v32, v32 row_ror:4 row_mask:0xf bank_mask:0xf
	s_nop 1
	v_add_f32_dpp v32, v32, v32 row_ror:2 row_mask:0xf bank_mask:0xf
	s_nop 1
	v_add_f32_dpp v32, v32, v32 row_ror:1 row_mask:0xf bank_mask:0xf
	v_fmamk_f32 v32, v32, 0x3a800000, v200
	v_rsq_f32_e32 v32, v32
	s_waitcnt vmcnt(0)
	v_pk_add_f32 v[72:73], v[72:73], 1.0 op_sel_hi:[1,0]
	v_pk_mul_f32 v[76:77], v[14:15], v[32:33] op_sel_hi:[1,0]
	v_pk_mul_f32 v[78:79], v[12:13], v[32:33] op_sel_hi:[1,0]
	v_pk_mul_f32 v[66:67], v[66:67], v[76:77]
	v_pk_mul_f32 v[64:65], v[64:65], v[78:79]
	v_add_co_u32_e32 v76, vcc, s25, v46
	v_pk_add_f32 v[74:75], v[74:75], 1.0 op_sel_hi:[1,0]
	v_pk_fma_f32 v[64:65], v[72:73], v[64:65], v[68:69]
	v_addc_co_u32_e32 v77, vcc, -1, v47, vcc
	v_pk_fma_f32 v[66:67], v[74:75], v[66:67], v[70:71]
	v_cvt_pk_bf16_f32 v64, v64, v65
	v_pk_mul_f32 v[80:81], v[8:9], v[32:33] op_sel_hi:[1,0]
	v_cvt_pk_bf16_f32 v65, v66, v67
	global_store_dwordx2 v[76:77], v[64:65], off offset:-1536
	global_load_dwordx4 v[64:67], v[44:45], off offset:1024
	s_nop 0
	global_load_dwordx4 v[68:71], v160, s[26:27] offset:1024
	global_load_dwordx4 v[72:75], v[34:35], off offset:1024
	v_pk_mul_f32 v[78:79], v[10:11], v[32:33] op_sel_hi:[1,0]
	s_waitcnt vmcnt(2)
	v_pk_mul_f32 v[64:65], v[64:65], v[80:81]
	v_pk_mul_f32 v[66:67], v[66:67], v[78:79]
	s_waitcnt vmcnt(0)
	v_pk_add_f32 v[72:73], v[72:73], 1.0 op_sel_hi:[1,0]
	v_pk_add_f32 v[74:75], v[74:75], 1.0 op_sel_hi:[1,0]
	v_pk_fma_f32 v[64:65], v[64:65], v[72:73], v[68:69]
	v_pk_fma_f32 v[66:67], v[66:67], v[74:75], v[70:71]
	v_cvt_pk_bf16_f32 v64, v64, v65
	v_pk_mul_f32 v[80:81], v[4:5], v[32:33] op_sel_hi:[1,0]
	v_cvt_pk_bf16_f32 v65, v66, v67
	global_store_dwordx2 v[76:77], v[64:65], off offset:-1024
	global_load_dwordx4 v[64:67], v[44:45], off offset:2048
	s_nop 0
	global_load_dwordx4 v[68:71], v160, s[26:27] offset:2048
	global_load_dwordx4 v[72:75], v[34:35], off offset:2048
	v_pk_mul_f32 v[78:79], v[6:7], v[32:33] op_sel_hi:[1,0]
	s_waitcnt vmcnt(2)
	v_pk_mul_f32 v[64:65], v[80:81], v[64:65]
	v_pk_mul_f32 v[66:67], v[78:79], v[66:67]
	s_waitcnt vmcnt(0)
	v_pk_add_f32 v[72:73], v[72:73], 1.0 op_sel_hi:[1,0]
	v_pk_add_f32 v[74:75], v[74:75], 1.0 op_sel_hi:[1,0]
	v_pk_fma_f32 v[64:65], v[64:65], v[72:73], v[68:69]
	v_pk_fma_f32 v[66:67], v[66:67], v[74:75], v[70:71]
	v_cvt_pk_bf16_f32 v64, v64, v65
	s_nop 0
	v_cvt_pk_bf16_f32 v65, v66, v67
	global_store_dwordx2 v[76:77], v[64:65], off offset:-512
	global_load_dwordx4 v[64:67], v[44:45], off offset:3072
	s_nop 0
	global_load_dwordx4 v[68:71], v160, s[26:27] offset:3072
	global_load_dwordx4 v[72:75], v[34:35], off offset:3072
	v_pk_mul_f32 v[34:35], v[2:3], v[32:33] op_sel_hi:[1,0]
	v_pk_mul_f32 v[32:33], v[0:1], v[32:33] op_sel_hi:[1,0]
	s_waitcnt vmcnt(2)
	v_pk_mul_f32 v[34:35], v[34:35], v[66:67]
	v_pk_mul_f32 v[32:33], v[32:33], v[64:65]
	s_waitcnt vmcnt(0)
	v_pk_add_f32 v[66:67], v[72:73], 1.0 op_sel_hi:[1,0]
	v_pk_add_f32 v[64:65], v[74:75], 1.0 op_sel_hi:[1,0]
	v_pk_fma_f32 v[32:33], v[32:33], v[66:67], v[68:69]
	v_pk_fma_f32 v[34:35], v[34:35], v[64:65], v[70:71]
	v_cvt_pk_bf16_f32 v32, v32, v33
	s_nop 0
	v_cvt_pk_bf16_f32 v33, v34, v35
	global_store_dwordx2 v[76:77], v[32:33], off
.LBB0_156:
	s_and_b64 vcc, exec, s[10:11]
	s_cbranch_vccnz .LBB0_148
	s_waitcnt vmcnt(3)
	v_and_b32_e32 v77, 0xffff0000, v63
	v_and_b32_e32 v76, 0xffff0000, v62
	v_lshlrev_b32_e32 v75, 16, v63
	v_lshlrev_b32_e32 v74, 16, v62
	v_pk_mul_f32 v[32:33], v[76:77], v[76:77]
	s_waitcnt vmcnt(2)
	v_and_b32_e32 v73, 0xffff0000, v61
	v_pk_fma_f32 v[32:33], v[74:75], v[74:75], v[32:33]
	v_and_b32_e32 v72, 0xffff0000, v60
	v_pk_add_f32 v[68:69], v[32:33], v[32:33] op_sel_hi:[0,1]
	v_lshlrev_b32_e32 v71, 16, v61
	v_lshlrev_b32_e32 v70, 16, v60
	v_pk_mul_f32 v[32:33], v[72:73], v[72:73]
	s_waitcnt vmcnt(1)
	v_lshlrev_b32_e32 v34, 16, v59
	v_pk_fma_f32 v[32:33], v[70:71], v[70:71], v[32:33]
	v_and_b32_e32 v35, 0xffff0000, v59
	v_pk_add_f32 v[78:79], v[32:33], v[32:33] op_sel_hi:[0,1]
	v_lshlrev_b32_e32 v32, 16, v58
	v_mul_f32_e32 v65, v32, v32
	v_mul_f32_e32 v64, v34, v34
	v_and_b32_e32 v33, 0xffff0000, v58
	v_pk_fma_f32 v[84:85], v[34:35], v[34:35], v[64:65] op_sel_hi:[1,1,0]
	s_waitcnt vmcnt(0)
	v_lshlrev_b32_e32 v64, 16, v56
	v_mul_f32_e32 v81, v33, v33
	v_mov_b32_e32 v80, v64
	v_and_b32_e32 v82, 0xffff0000, v56
	v_lshlrev_b32_e32 v66, 16, v57
	v_and_b32_e32 v67, 0xffff0000, v57
	v_pk_add_f32 v[80:81], v[64:65], v[80:81]
	v_mul_f32_e32 v84, v82, v82
	v_mul_f32_e32 v78, v66, v66
	v_mul_f32_e32 v68, v67, v67
	v_mul_f32_e32 v86, v64, v64
	v_mov_b32_e32 v87, v81
	v_pk_add_f32 v[80:81], v[86:87], v[84:85]
	v_pk_add_f32 v[68:69], v[78:79], v[68:69]
	v_cmp_lt_i32_e32 vcc, v205, v204
	v_pk_add_f32 v[68:69], v[80:81], v[68:69]
	s_and_b64 s[10:11], s[64:65], exec
	v_cndmask_b32_e32 v37, v203, v205, vcc
	v_add_f32_e32 v65, v68, v69
	v_lshlrev_b32_e32 v37, 2, v37
	v_cmp_lt_i32_e32 vcc, v206, v204
	s_cselect_b32 s10, s62, 8
	s_add_i32 s11, s10, s3
	s_mul_hi_i32 s25, s11, 0x6000
	v_mov_b32_e32 v68, v65
	s_nop 1
	v_permlane32_swap_b32_e32 v68, v65
	v_add_f32_e32 v65, v65, v68
	v_cndmask_b32_e32 v68, v203, v206, vcc
	v_lshlrev_b32_e32 v69, 2, v68
	v_cmp_lt_i32_e32 vcc, v207, v204
	s_mulk_i32 s11, 0x6000
	s_add_u32 s26, s34, s11
	s_addc_u32 s27, s35, s25
	v_mov_b32_e32 v68, v65
	s_nop 1
	v_permlane16_swap_b32_e32 v68, v65
	v_add_f32_e32 v65, v65, v68
	v_cndmask_b32_e32 v68, v203, v207, vcc
	v_lshlrev_b32_e32 v78, 2, v68
	v_cmp_lt_i32_e32 vcc, v208, v204
	v_lshl_add_u64 v[84:85], s[26:27], 0, v[160:161]
	s_mov_b64 s[26:27], 0x5000
	s_movk_i32 s11, 0x5000
	s_nop 1
	v_add_f32_dpp v65, v65, v65 row_ror:8 row_mask:0xf bank_mask:0xf
	v_cndmask_b32_e32 v68, v203, v208, vcc
	v_lshlrev_b32_e32 v79, 2, v68
	v_cmp_lt_i32_e32 vcc, v209, v204
	v_lshl_add_u64 v[92:93], v[84:85], 0, s[26:27]
	v_mov_b32_e32 v94, v75
	v_mov_b32_e32 v95, v77
	s_nop 1
	v_add_f32_dpp v65, v65, v65 row_ror:4 row_mask:0xf bank_mask:0xf
	v_cndmask_b32_e32 v68, v203, v209, vcc
	v_lshlrev_b32_e32 v80, 2, v68
	v_cmp_lt_i32_e32 vcc, v210, v204
	v_mov_b32_e32 v75, v76
	s_nop 1
	v_add_f32_dpp v65, v65, v65 row_ror:2 row_mask:0xf bank_mask:0xf
	v_cndmask_b32_e32 v68, v203, v210, vcc
	v_add_co_u32_e32 v84, vcc, s11, v84
	v_lshlrev_b32_e32 v81, 2, v68
	s_nop 0
	v_addc_co_u32_e32 v85, vcc, 0, v85, vcc
	global_load_dwordx4 v[84:87], v[84:85], off
	s_nop 0
	global_load_dwordx4 v[88:91], v[42:43], off
	s_and_b64 vcc, exec, s[8:9]
	s_nop 1
	v_add_f32_dpp v65, v65, v65 row_ror:1 row_mask:0xf bank_mask:0xf
	v_fmamk_f32 v65, v65, 0x3a800000, v200
	v_rsq_f32_e32 v68, v65
	v_mov_b32_e32 v65, v82
	v_pk_mul_f32 v[94:95], v[68:69], v[94:95] op_sel_hi:[0,1]
	v_pk_mul_f32 v[74:75], v[68:69], v[74:75] op_sel_hi:[0,1]
	v_pk_mul_f32 v[34:35], v[34:35], v[68:69] op_sel_hi:[1,0]
	v_pk_mul_f32 v[32:33], v[32:33], v[68:69] op_sel_hi:[1,0]
	v_pk_mul_f32 v[66:67], v[66:67], v[68:69] op_sel_hi:[1,0]
	v_pk_mul_f32 v[64:65], v[64:65], v[68:69] op_sel_hi:[1,0]
	s_waitcnt vmcnt(0)
	v_pk_mul_f32 v[74:75], v[88:89], v[74:75]
	v_pk_mul_f32 v[76:77], v[90:91], v[94:95]
	v_pk_fma_f32 v[16:17], v[84:85], v[74:75], v[16:17]
	v_pk_fma_f32 v[18:19], v[86:87], v[76:77], v[18:19]
	global_load_dwordx4 v[74:77], v[92:93], off offset:1024
	global_load_dwordx4 v[84:87], v[42:43], off offset:1024
	v_mov_b32_e32 v88, v71
	v_mov_b32_e32 v89, v73
	v_mov_b32_e32 v71, v72
	v_pk_mul_f32 v[88:89], v[68:69], v[88:89] op_sel_hi:[0,1]
	v_pk_mul_f32 v[70:71], v[68:69], v[70:71] op_sel_hi:[0,1]
	s_waitcnt vmcnt(0)
	v_pk_mul_f32 v[70:71], v[84:85], v[70:71]
	v_pk_mul_f32 v[72:73], v[86:87], v[88:89]
	v_pk_fma_f32 v[20:21], v[74:75], v[70:71], v[20:21]
	v_pk_fma_f32 v[22:23], v[76:77], v[72:73], v[22:23]
	global_load_dwordx4 v[70:73], v[92:93], off offset:2048
	global_load_dwordx4 v[74:77], v[42:43], off offset:2048
	s_waitcnt vmcnt(0)
	v_pk_mul_f32 v[32:33], v[74:75], v[32:33]
	v_pk_mul_f32 v[34:35], v[76:77], v[34:35]
	v_pk_fma_f32 v[24:25], v[70:71], v[32:33], v[24:25]
	v_pk_fma_f32 v[26:27], v[72:73], v[34:35], v[26:27]
	global_load_dwordx4 v[32:35], v[92:93], off offset:3072
	global_load_dwordx4 v[70:73], v[42:43], off offset:3072
	s_waitcnt vmcnt(0)
	v_pk_mul_f32 v[64:65], v[64:65], v[70:71]
	v_pk_mul_f32 v[66:67], v[66:67], v[72:73]
	v_pk_fma_f32 v[28:29], v[32:33], v[64:65], v[28:29]
	v_pk_fma_f32 v[30:31], v[34:35], v[66:67], v[30:31]
	global_store_dwordx4 v160, v[16:19], s[6:7] nt
	global_store_dwordx4 v160, v[20:23], s[6:7] offset:1024 nt
	global_store_dwordx4 v160, v[24:27], s[6:7] offset:2048 nt
	global_store_dwordx4 v160, v[28:31], s[6:7] offset:3072 nt
	s_cbranch_vccnz .LBB0_148
	v_pk_mul_f32 v[32:33], v[18:19], v[18:19]
	v_pk_mul_f32 v[34:35], v[16:17], v[16:17]
	s_add_i32 s6, s10, s13
	v_pk_mov_b32 v[64:65], v[34:35], v[32:33] op_sel:[1,0]
	v_mov_b32_e32 v35, v33
	v_pk_add_f32 v[32:33], v[64:65], v[34:35]
	v_pk_mul_f32 v[34:35], v[22:23], v[22:23]
	v_pk_add_f32 v[32:33], v[32:33], v[32:33] op_sel_hi:[0,1]
	v_pk_mul_f32 v[64:65], v[20:21], v[20:21]
	v_mul_f32_e32 v32, v24, v24
	v_pk_mov_b32 v[66:67], v[64:65], v[34:35] op_sel:[1,0]
	v_mov_b32_e32 v65, v35
	v_pk_add_f32 v[34:35], v[66:67], v[64:65]
	v_pk_fma_f32 v[64:65], v[24:25], v[24:25], v[32:33] op_sel_hi:[1,1,0]
	v_mul_f32_e32 v32, v26, v26
	v_pk_add_f32 v[34:35], v[34:35], v[34:35] op_sel_hi:[0,1]
	v_pk_fma_f32 v[66:67], v[26:27], v[26:27], v[32:33] op_sel_hi:[1,1,0]
	v_mul_f32_e32 v64, v28, v28
	v_mul_f32_e32 v66, v29, v29
	v_mul_f32_e32 v32, v30, v30
	v_mul_f32_e32 v34, v31, v31
	v_pk_add_f32 v[64:65], v[64:65], v[66:67]
	v_pk_add_f32 v[32:33], v[32:33], v[34:35]
	s_mul_hi_i32 s7, s6, 0x6000
	v_pk_add_f32 v[32:33], v[64:65], v[32:33]
	s_mulk_i32 s6, 0x6000
	v_add_f32_e32 v32, v32, v33
	s_add_u32 s6, s34, s6
	s_addc_u32 s7, s35, s7
	v_lshl_add_u64 v[74:75], s[6:7], 0, v[160:161]
	v_lshl_add_u64 v[64:65], v[74:75], 0, s[30:31]
	v_add_co_u32_e32 v74, vcc, s58, v74
	v_mov_b32_e32 v33, v32
	s_nop 1
	v_permlane32_swap_b32_e32 v33, v32
	v_add_f32_e32 v32, v32, v33
	v_addc_co_u32_e32 v75, vcc, 0, v75, vcc
	global_load_dwordx4 v[66:69], v[44:45], off
	global_load_dwordx4 v[70:73], v160, s[6:7]
	s_ashr_i32 s39, s38, 31
	global_load_dwordx4 v[74:77], v[74:75], off
	s_lshl_b64 s[8:9], s[38:39], 11
	v_mov_b32_e32 v33, v32
	s_nop 1
	v_permlane16_swap_b32_e32 v33, v32
	v_add_f32_e32 v32, v32, v33
	v_lshl_add_u64 v[34:35], v[40:41], 0, s[8:9]
	s_nop 1
	v_add_f32_dpp v32, v32, v32 row_ror:8 row_mask:0xf bank_mask:0xf
	s_nop 1
	v_add_f32_dpp v32, v32, v32 row_ror:4 row_mask:0xf bank_mask:0xf
	s_nop 1
	v_add_f32_dpp v32, v32, v32 row_ror:2 row_mask:0xf bank_mask:0xf
	s_nop 1
	v_add_f32_dpp v32, v32, v32 row_ror:1 row_mask:0xf bank_mask:0xf
	v_fmamk_f32 v32, v32, 0x3a800000, v200
	v_rsq_f32_e32 v32, v32
	s_waitcnt vmcnt(0)
	v_pk_add_f32 v[74:75], v[74:75], 1.0 op_sel_hi:[1,0]
	v_pk_mul_f32 v[80:81], v[16:17], v[32:33] op_sel_hi:[1,0]
	v_pk_mul_f32 v[78:79], v[18:19], v[32:33] op_sel_hi:[1,0]
	v_pk_mul_f32 v[66:67], v[66:67], v[80:81]
	v_pk_mul_f32 v[68:69], v[68:69], v[78:79]
	v_pk_add_f32 v[76:77], v[76:77], 1.0 op_sel_hi:[1,0]
	v_pk_fma_f32 v[66:67], v[74:75], v[66:67], v[70:71]
	v_pk_fma_f32 v[68:69], v[76:77], v[68:69], v[72:73]
	v_cvt_pk_bf16_f32 v66, v66, v67
	v_pk_mul_f32 v[80:81], v[20:21], v[32:33] op_sel_hi:[1,0]
	v_cvt_pk_bf16_f32 v67, v68, v69
	global_store_dwordx2 v[34:35], v[66:67], off
	global_load_dwordx4 v[66:69], v[44:45], off offset:1024
	s_nop 0
	global_load_dwordx4 v[70:73], v160, s[6:7] offset:1024
	global_load_dwordx4 v[74:77], v[64:65], off offset:1024
	v_pk_mul_f32 v[78:79], v[22:23], v[32:33] op_sel_hi:[1,0]
	s_waitcnt vmcnt(2)
	v_pk_mul_f32 v[66:67], v[66:67], v[80:81]
	v_pk_mul_f32 v[68:69], v[68:69], v[78:79]
	s_waitcnt vmcnt(0)
	v_pk_add_f32 v[74:75], v[74:75], 1.0 op_sel_hi:[1,0]
	v_pk_add_f32 v[76:77], v[76:77], 1.0 op_sel_hi:[1,0]
	v_pk_fma_f32 v[66:67], v[66:67], v[74:75], v[70:71]
	v_pk_fma_f32 v[68:69], v[68:69], v[76:77], v[72:73]
	v_cvt_pk_bf16_f32 v66, v66, v67
	v_pk_mul_f32 v[80:81], v[24:25], v[32:33] op_sel_hi:[1,0]
	v_cvt_pk_bf16_f32 v67, v68, v69
	global_store_dwordx2 v[34:35], v[66:67], off offset:512
	global_load_dwordx4 v[66:69], v[44:45], off offset:2048
	s_nop 0
	global_load_dwordx4 v[70:73], v160, s[6:7] offset:2048
	global_load_dwordx4 v[74:77], v[64:65], off offset:2048
	v_pk_mul_f32 v[78:79], v[26:27], v[32:33] op_sel_hi:[1,0]
	s_waitcnt vmcnt(2)
	v_pk_mul_f32 v[66:67], v[80:81], v[66:67]
	v_pk_mul_f32 v[68:69], v[78:79], v[68:69]
	s_waitcnt vmcnt(0)
	v_pk_add_f32 v[74:75], v[74:75], 1.0 op_sel_hi:[1,0]
	v_pk_add_f32 v[76:77], v[76:77], 1.0 op_sel_hi:[1,0]
	v_pk_fma_f32 v[66:67], v[66:67], v[74:75], v[70:71]
	v_pk_fma_f32 v[68:69], v[68:69], v[76:77], v[72:73]
	v_cvt_pk_bf16_f32 v66, v66, v67
	s_nop 0
	v_cvt_pk_bf16_f32 v67, v68, v69
	global_store_dwordx2 v[34:35], v[66:67], off offset:1024
	global_load_dwordx4 v[66:69], v[44:45], off offset:3072
	s_nop 0
	global_load_dwordx4 v[70:73], v160, s[6:7] offset:3072
	global_load_dwordx4 v[74:77], v[64:65], off offset:3072
	v_pk_mul_f32 v[64:65], v[30:31], v[32:33] op_sel_hi:[1,0]
	v_pk_mul_f32 v[32:33], v[28:29], v[32:33] op_sel_hi:[1,0]
	s_waitcnt vmcnt(2)
	v_pk_mul_f32 v[64:65], v[64:65], v[68:69]
	v_pk_mul_f32 v[32:33], v[32:33], v[66:67]
	s_waitcnt vmcnt(0)
	v_pk_add_f32 v[68:69], v[74:75], 1.0 op_sel_hi:[1,0]
	v_pk_add_f32 v[66:67], v[76:77], 1.0 op_sel_hi:[1,0]
	v_pk_fma_f32 v[32:33], v[32:33], v[68:69], v[70:71]
	v_pk_fma_f32 v[64:65], v[64:65], v[66:67], v[72:73]
	v_cvt_pk_bf16_f32 v32, v32, v33
	s_nop 0
	v_cvt_pk_bf16_f32 v33, v64, v65
	global_store_dwordx2 v[34:35], v[32:33], off offset:1536
	s_branch .LBB0_148

.Lr1_nocopy:
	s_waitcnt vmcnt(20)
	v_pk_mul_f32 v[58:59], v[30:31], v[30:31]
	v_pk_mul_f32 v[60:61], v[28:29], v[28:29]
	v_mul_f32_e32 v43, v16, v16
	v_pk_mov_b32 v[62:63], v[60:61], v[58:59] op_sel:[1,0]
	v_mov_b32_e32 v61, v59
	v_pk_add_f32 v[58:59], v[62:63], v[60:61]
	v_pk_mul_f32 v[60:61], v[26:27], v[26:27]
	v_pk_mul_f32 v[62:63], v[24:25], v[24:25]
	v_pk_add_f32 v[58:59], v[58:59], v[58:59] op_sel:[0,1] op_sel_hi:[1,0]
	v_pk_mov_b32 v[64:65], v[62:63], v[60:61] op_sel:[1,0]
	v_mov_b32_e32 v63, v61
	v_pk_add_f32 v[60:61], v[64:65], v[62:63]
	v_mul_f32_e32 v62, v17, v17
	v_pk_add_f32 v[60:61], v[60:61], v[60:61] op_sel:[0,1] op_sel_hi:[1,0]
	v_mov_b32_e32 v59, v43
	v_mov_b32_e32 v61, v62
	v_pk_add_f32 v[58:59], v[58:59], v[60:61]
	v_mul_f32_e32 v60, v21, v21
	v_mul_f32_e32 v63, v18, v18
	v_pk_fma_f32 v[60:61], v[20:21], v[20:21], v[60:61] op_sel_hi:[1,1,0]
	v_mul_f32_e32 v62, v23, v23
	v_mul_f32_e32 v64, v19, v19
	v_mov_b32_e32 v61, v63
	v_pk_fma_f32 v[62:63], v[22:23], v[22:23], v[62:63] op_sel_hi:[1,1,0]
	s_nop 0
	v_mov_b32_e32 v63, v64
	v_pk_add_f32 v[60:61], v[60:61], v[62:63]
	s_nop 0
	v_pk_add_f32 v[58:59], v[58:59], v[60:61]
	s_nop 0
	v_add_f32_e32 v43, v58, v59
	v_mov_b32_e32 v58, v43
	s_nop 1
	v_permlane32_swap_b32_e32 v58, v43
	v_add_f32_e32 v43, v43, v58
	v_mov_b32_e32 v58, v43
	s_nop 1
	v_permlane16_swap_b32_e32 v58, v43
	v_add_f32_e32 v43, v43, v58
	s_nop 1
	v_add_f32_dpp v43, v43, v43 row_ror:8 row_mask:0xf bank_mask:0xf
	s_nop 1
	v_add_f32_dpp v43, v43, v43 row_ror:4 row_mask:0xf bank_mask:0xf
	s_nop 1
	v_add_f32_dpp v43, v43, v43 row_ror:2 row_mask:0xf bank_mask:0xf
	v_lshl_add_u64 v[58:59], s[10:11], 0, v[36:37]
	v_add_co_u32_e32 v58, vcc, s95, v58
	s_nop 1
	v_add_f32_dpp v43, v43, v43 row_ror:1 row_mask:0xf bank_mask:0xf
	v_fmamk_f32 v43, v43, 0x3a800000, v200
	v_rsq_f32_e32 v60, v43
	v_addc_co_u32_e32 v59, vcc, 0, v59, vcc
	s_andn2_b64 vcc, exec, s[20:21]
	v_pk_mul_f32 v[28:29], v[28:29], v[60:61] op_sel_hi:[1,0]
	v_pk_mul_f32 v[30:31], v[30:31], v[60:61] op_sel_hi:[1,0]
	v_pk_mul_f32 v[28:29], v[238:239], v[28:29]
	v_pk_mul_f32 v[30:31], v[240:241], v[30:31]
	s_waitcnt vmcnt(14)
	v_pk_add_f32 v[172:173], v[172:173], 1.0 op_sel_hi:[1,0]
	v_pk_add_f32 v[174:175], v[174:175], 1.0 op_sel_hi:[1,0]
	v_pk_fma_f32 v[28:29], v[172:173], v[28:29], v[176:177]
	v_pk_fma_f32 v[30:31], v[174:175], v[30:31], v[178:179]
	v_cvt_pk_bf16_f32 v28, v28, v29
	s_nop 0
	v_cvt_pk_bf16_f32 v29, v30, v31
	global_store_dwordx2 v[58:59], v[28:29], off
	v_pk_mul_f32 v[24:25], v[24:25], v[60:61] op_sel_hi:[1,0]
	v_pk_mul_f32 v[26:27], v[26:27], v[60:61] op_sel_hi:[1,0]
	v_pk_mul_f32 v[24:25], v[242:243], v[24:25]
	v_pk_mul_f32 v[26:27], v[244:245], v[26:27]
	s_waitcnt vmcnt(13)
	v_pk_add_f32 v[180:181], v[180:181], 1.0 op_sel_hi:[1,0]
	v_pk_add_f32 v[182:183], v[182:183], 1.0 op_sel_hi:[1,0]
	v_pk_fma_f32 v[24:25], v[180:181], v[24:25], v[184:185]
	v_pk_fma_f32 v[26:27], v[182:183], v[26:27], v[186:187]
	v_cvt_pk_bf16_f32 v24, v24, v25
	s_nop 0
	v_cvt_pk_bf16_f32 v25, v26, v27
	global_store_dwordx2 v[58:59], v[24:25], off offset:512
	v_pk_mul_f32 v[20:21], v[20:21], v[60:61] op_sel_hi:[1,0]
	v_pk_mul_f32 v[22:23], v[22:23], v[60:61] op_sel_hi:[1,0]
	v_pk_mul_f32 v[20:21], v[246:247], v[20:21]
	v_pk_mul_f32 v[22:23], v[248:249], v[22:23]
	s_waitcnt vmcnt(12)
	v_pk_add_f32 v[188:189], v[188:189], 1.0 op_sel_hi:[1,0]
	v_pk_add_f32 v[190:191], v[190:191], 1.0 op_sel_hi:[1,0]
	v_pk_fma_f32 v[20:21], v[188:189], v[20:21], v[192:193]
	v_pk_fma_f32 v[22:23], v[190:191], v[22:23], v[194:195]
	v_cvt_pk_bf16_f32 v20, v20, v21
	s_nop 0
	v_cvt_pk_bf16_f32 v21, v22, v23
	global_store_dwordx2 v[58:59], v[20:21], off offset:1024
	v_pk_mul_f32 v[16:17], v[16:17], v[60:61] op_sel_hi:[1,0]
	v_pk_mul_f32 v[18:19], v[18:19], v[60:61] op_sel_hi:[1,0]
	v_pk_mul_f32 v[16:17], v[250:251], v[16:17]
	v_pk_mul_f32 v[18:19], v[252:253], v[18:19]
	s_waitcnt vmcnt(11)
	v_pk_add_f32 v[196:197], v[196:197], 1.0 op_sel_hi:[1,0]
	v_pk_add_f32 v[198:199], v[198:199], 1.0 op_sel_hi:[1,0]
	v_pk_fma_f32 v[16:17], v[196:197], v[16:17], v[218:219]
	v_pk_fma_f32 v[18:19], v[198:199], v[18:19], v[220:221]
	v_cvt_pk_bf16_f32 v16, v16, v17
	s_nop 0
	v_cvt_pk_bf16_f32 v17, v18, v19
	global_store_dwordx2 v[58:59], v[16:17], off offset:1536
	s_cbranch_vccnz .Lr1_binv
	v_pk_mul_f32 v[58:59], v[2:3], v[2:3]
	v_pk_mul_f32 v[60:61], v[0:1], v[0:1]
	v_mul_f32_e32 v43, v12, v12
	v_pk_mov_b32 v[62:63], v[60:61], v[58:59] op_sel:[1,0]
	v_mov_b32_e32 v61, v59
	v_pk_add_f32 v[58:59], v[62:63], v[60:61]
	v_pk_mul_f32 v[60:61], v[6:7], v[6:7]
	v_pk_mul_f32 v[62:63], v[4:5], v[4:5]
	v_pk_add_f32 v[58:59], v[58:59], v[58:59] op_sel:[0,1] op_sel_hi:[1,0]
	v_pk_mov_b32 v[64:65], v[62:63], v[60:61] op_sel:[1,0]
	v_mov_b32_e32 v63, v61
	v_pk_add_f32 v[60:61], v[64:65], v[62:63]
	v_mul_f32_e32 v62, v13, v13
	v_pk_add_f32 v[60:61], v[60:61], v[60:61] op_sel:[0,1] op_sel_hi:[1,0]
	v_mov_b32_e32 v59, v43
	v_mov_b32_e32 v61, v62
	v_pk_add_f32 v[58:59], v[58:59], v[60:61]
	v_mul_f32_e32 v60, v9, v9
	v_mul_f32_e32 v63, v14, v14
	v_pk_fma_f32 v[60:61], v[8:9], v[8:9], v[60:61] op_sel_hi:[1,1,0]
	v_mul_f32_e32 v62, v11, v11
	v_mul_f32_e32 v64, v15, v15
	v_mov_b32_e32 v61, v63
	v_pk_fma_f32 v[62:63], v[10:11], v[10:11], v[62:63] op_sel_hi:[1,1,0]
	s_nop 0
	v_mov_b32_e32 v63, v64
	v_pk_add_f32 v[60:61], v[60:61], v[62:63]
	s_nop 0
	v_pk_add_f32 v[58:59], v[58:59], v[60:61]
	s_nop 0
	v_add_f32_e32 v43, v58, v59
	v_mov_b32_e32 v58, v43
	s_nop 1
	v_permlane32_swap_b32_e32 v58, v43
	v_add_f32_e32 v43, v43, v58
	v_mov_b32_e32 v58, v43
	s_nop 1
	v_permlane16_swap_b32_e32 v58, v43
	v_add_f32_e32 v43, v43, v58
	s_nop 1
	v_add_f32_dpp v43, v43, v43 row_ror:8 row_mask:0xf bank_mask:0xf
	s_nop 1
	v_add_f32_dpp v43, v43, v43 row_ror:4 row_mask:0xf bank_mask:0xf
	s_nop 1
	v_add_f32_dpp v43, v43, v43 row_ror:2 row_mask:0xf bank_mask:0xf
	v_lshl_add_u64 v[58:59], s[12:13], 0, v[36:37]
	v_add_co_u32_e32 v58, vcc, s95, v58
	s_nop 1
	v_add_f32_dpp v43, v43, v43 row_ror:1 row_mask:0xf bank_mask:0xf
	v_fmamk_f32 v43, v43, 0x3a800000, v200
	v_rsq_f32_e32 v60, v43
	v_addc_co_u32_e32 v59, vcc, 0, v59, vcc
	s_nop 0
	v_pk_mul_f32 v[0:1], v[0:1], v[60:61] op_sel_hi:[1,0]
	v_pk_mul_f32 v[2:3], v[2:3], v[60:61] op_sel_hi:[1,0]
	v_pk_mul_f32 v[0:1], v[238:239], v[0:1]
	v_pk_mul_f32 v[2:3], v[240:241], v[2:3]
	s_waitcnt vmcnt(10)
	v_pk_add_f32 v[222:223], v[222:223], 1.0 op_sel_hi:[1,0]
	v_pk_add_f32 v[224:225], v[224:225], 1.0 op_sel_hi:[1,0]
	v_pk_fma_f32 v[0:1], v[222:223], v[0:1], v[226:227]
	v_pk_fma_f32 v[2:3], v[224:225], v[2:3], v[228:229]
	v_cvt_pk_bf16_f32 v0, v0, v1
	s_nop 0
	v_cvt_pk_bf16_f32 v1, v2, v3
	global_store_dwordx2 v[58:59], v[0:1], off
	v_pk_mul_f32 v[4:5], v[4:5], v[60:61] op_sel_hi:[1,0]
	v_pk_mul_f32 v[6:7], v[6:7], v[60:61] op_sel_hi:[1,0]
	v_pk_mul_f32 v[4:5], v[242:243], v[4:5]
	v_pk_mul_f32 v[6:7], v[244:245], v[6:7]
	s_waitcnt vmcnt(9)
	v_pk_add_f32 v[230:231], v[230:231], 1.0 op_sel_hi:[1,0]
	v_pk_add_f32 v[232:233], v[232:233], 1.0 op_sel_hi:[1,0]
	v_pk_fma_f32 v[4:5], v[230:231], v[4:5], v[234:235]
	v_pk_fma_f32 v[6:7], v[232:233], v[6:7], v[236:237]
	v_cvt_pk_bf16_f32 v4, v4, v5
	s_nop 0
	v_cvt_pk_bf16_f32 v5, v6, v7
	global_store_dwordx2 v[58:59], v[4:5], off offset:512
	v_pk_mul_f32 v[8:9], v[8:9], v[60:61] op_sel_hi:[1,0]
	v_pk_mul_f32 v[10:11], v[10:11], v[60:61] op_sel_hi:[1,0]
	v_pk_mul_f32 v[8:9], v[246:247], v[8:9]
	v_pk_mul_f32 v[10:11], v[248:249], v[10:11]
	s_waitcnt vmcnt(8)
	v_pk_add_f32 v[44:45], v[44:45], 1.0 op_sel_hi:[1,0]
	v_pk_add_f32 v[46:47], v[46:47], 1.0 op_sel_hi:[1,0]
	v_pk_fma_f32 v[8:9], v[44:45], v[8:9], v[48:49]
	v_pk_fma_f32 v[10:11], v[46:47], v[10:11], v[50:51]
	v_cvt_pk_bf16_f32 v8, v8, v9
	s_nop 0
	v_cvt_pk_bf16_f32 v9, v10, v11
	global_store_dwordx2 v[58:59], v[8:9], off offset:1024
	v_pk_mul_f32 v[12:13], v[12:13], v[60:61] op_sel_hi:[1,0]
	v_pk_mul_f32 v[14:15], v[14:15], v[60:61] op_sel_hi:[1,0]
	v_pk_mul_f32 v[12:13], v[250:251], v[12:13]
	v_pk_mul_f32 v[14:15], v[252:253], v[14:15]
	s_waitcnt vmcnt(7)
	v_pk_add_f32 v[52:53], v[52:53], 1.0 op_sel_hi:[1,0]
	v_pk_add_f32 v[54:55], v[54:55], 1.0 op_sel_hi:[1,0]
	v_pk_fma_f32 v[12:13], v[52:53], v[12:13], v[164:165]
	v_pk_fma_f32 v[14:15], v[54:55], v[14:15], v[166:167]
	v_cvt_pk_bf16_f32 v12, v12, v13
	s_nop 0
	v_cvt_pk_bf16_f32 v13, v14, v15
	global_store_dwordx2 v[58:59], v[12:13], off offset:1536
	s_branch .LBB0_367
